# phase_norm loops software pipelined: next row's x loads issued behind the current row's parameter loads (double-buffered in spare registers)
# speedup vs baseline: 1.0032x; 1.0001x over previous
; __device__ __forceinline__ void phase_norm(const Frame& F, const Params& P, int l, int which, int nrows, bf16_t* HB) {
;     const float* xl = (l == 0 && which == 0) ? P.in[0] : P.out; const float* xc = (l == 0 && which == 0) ? P.in[2] : (const float*)(P.ws + WS_XC);
;     const float* gn = P.in[6] + (l * 2 + which) * 1024; const float* MOD = (const float*)(P.ws + WS_MOD) + l * 5 * 6144;
;     bf16_t* H = (bf16_t*)(P.ws + WS_H);
;     const int gw = F.bid * 8 + F.wave, NGW = F.G * 8;
;     for (int row = gw; row < nrows; row += NGW) {
;         const float* xr = (row < NLAT) ? xl + (size_t)row * 1024 : xc + (size_t)(row - NLAT) * 1024;
;         const int mb = (row < NLAT) ? (row >> 13) : 4;
;         const float* sh = MOD + mb * 6144 + (which ? 3072 : 0); const float* sc = sh + 1024;
;         f32x4 v[4]; float ss = 0.f;
; #pragma unroll
;         for (int j = 0; j < 4; ++j) v[j] = *(const f32x4*)(xr + 4 * F.lane + 256 * j);
.LBB0_154:
	s_andn2_b64 vcc, exec, s[0:1]
	s_cbranch_vccnz .LBB0_370
	v_readlane_b32 s0, v253, 31
	s_cmp_lt_i32 s0, 8
	s_mov_b64 s[0:1], -1
	s_cbranch_scc1 .LBB0_210
	v_readlane_b32 s0, v253, 31
	s_cmp_gt_i32 s0, 8
	s_mov_b64 s[0:1], -1
	s_cbranch_scc0 .LBB0_171
	v_readlane_b32 s0, v254, 34
	v_readlane_b32 s1, v254, 35
	s_lshl_b32 s0, s0, 3
	v_readlane_b32 s1, v254, 37
	s_add_i32 s6, s0, s1
	v_readlane_b32 s0, v253, 35
	v_readlane_b32 s28, v251, 21
	s_cmp_ge_i32 s6, s0
	v_readlane_b32 s29, v251, 22
	s_cbranch_scc1 .LBB0_170
	s_add_u32 s2, s96, 0x15500000
	v_readlane_b32 s0, v254, 36
	v_lshlrev_b32_e32 v16, 2, v194
	s_addc_u32 s3, s97, 0
	s_lshl_b32 s8, s0, 3
	v_readlane_b32 s0, v253, 58
	v_or_b32_e32 v0, 0x100, v16
	v_readlane_b32 s1, v253, 59
	v_lshlrev_b32_e32 v2, 2, v0
	v_mov_b32_e32 v3, v193
	v_lshl_add_u64 v[24:25], s[0:1], 0, v[2:3]
	v_or_b32_e32 v2, 0x200, v16
	v_lshlrev_b32_e32 v4, 2, v2
	v_mov_b32_e32 v5, v193
	v_lshl_add_u64 v[26:27], s[0:1], 0, v[4:5]
	v_or_b32_e32 v4, 0x300, v16
	v_lshlrev_b32_e32 v192, 4, v194
	v_lshlrev_b32_e32 v6, 2, v4
	v_mov_b32_e32 v7, v193
	v_lshl_add_u64 v[22:23], s[0:1], 0, v[192:193]
	v_lshl_add_u64 v[28:29], s[0:1], 0, v[6:7]
	v_readlane_b32 s0, v251, 23
	v_readlane_b32 s1, v251, 24
	s_ashr_i32 s7, s6, 31
	v_readlane_b32 s12, v251, 46
	v_lshl_add_u64 v[30:31], s[0:1], 0, v[192:193]
	s_lshl_b64 s[0:1], s[6:7], 11
	v_readlane_b32 s9, v253, 11
	v_readlane_b32 s16, v251, 50
	v_readlane_b32 s17, v251, 51
	s_add_u32 s0, s9, s0
	v_readlane_b32 s9, v253, 12
	v_lshl_add_u64 v[18:19], s[16:17], 0, v[192:193]
	v_lshl_add_u64 v[20:21], s[28:29], 0, v[192:193]
	v_lshlrev_b32_e32 v192, 3, v194
	s_addc_u32 s1, s9, s1
	s_ashr_i32 s9, s8, 31
	v_lshl_add_u64 v[32:33], s[0:1], 0, v[192:193]
	s_lshl_b64 s[10:11], s[8:9], 11
	v_lshlrev_b32_e32 v17, 2, v0
	v_lshlrev_b32_e32 v38, 2, v2
	v_lshlrev_b32_e32 v39, 2, v4
	v_readlane_b32 s13, v251, 47
	v_readlane_b32 s14, v251, 48
	v_readlane_b32 s15, v251, 49
	v_readlane_b32 s18, v251, 52
	v_readlane_b32 s19, v251, 53
	v_readlane_b32 s20, v251, 54
	v_readlane_b32 s21, v251, 55
	v_readlane_b32 s22, v251, 56
	v_readlane_b32 s23, v251, 57
	v_readlane_b32 s24, v251, 58
	v_readlane_b32 s25, v251, 59
	v_readlane_b32 s26, v251, 60
	v_readlane_b32 s27, v251, 61
	v_lshlrev_b32_e32 v168, 2, v16
	s_add_i32 s17, s6, 0xffff8000
	v_readlane_b32 s18, v251, 6
	v_readlane_b32 s19, v251, 7
	s_cmp_lt_i32 s6, 0x8000
	s_cselect_b32 s18, s18, s28
	s_cselect_b32 s19, s19, s29
	s_cselect_b32 s16, s6, s17
	s_lshl_b32 s16, s16, 12
	s_add_u32 s18, s18, s16
	s_addc_u32 s19, s19, 0
	global_load_dwordx4 v[152:155], v168, s[18:19]
	global_load_dwordx4 v[156:159], v168, s[18:19] offset:1024
	global_load_dwordx4 v[160:163], v168, s[18:19] offset:2048
	global_load_dwordx4 v[164:167], v168, s[18:19] offset:3072
	s_waitcnt vmcnt(0)
	s_branch .LBB0_160

; __device__ __forceinline__ void phase_norm(const Frame& F, const Params& P, int l, int which, int nrows, bf16_t* HB) {
;     ...
;     for (int row = gw; row < nrows; row += NGW) {
;         const float* xr = (row < NLAT) ? xl + (size_t)row * 1024 : xc + (size_t)(row - NLAT) * 1024;
;         const int mb = (row < NLAT) ? (row >> 13) : 4;
;         const float* sh = MOD + mb * 6144 + (which ? 3072 : 0); const float* sc = sh + 1024;
;         f32x4 v[4]; float ss = 0.f;
; #pragma unroll
;         for (int j = 0; j < 4; ++j) v[j] = *(const f32x4*)(xr + 4 * F.lane + 256 * j);
;         if (l == 0 && which == 1 && row >= NLAT) {
;             const float* cin = P.in[2] + (size_t)(row - NLAT) * 1024 + 4 * F.lane;
;             const float* pp = (const float*)(P.ws + WS_AR + AR_PG4) + (size_t)(row - NLAT) * 1024 + 4 * F.lane;
;             float* xo = (float*)(P.ws + WS_XC) + (size_t)(row - NLAT) * 1024 + 4 * F.lane;
; #pragma unroll
;             for (int j = 0; j < 4; ++j) {
;                 v[j] = *(const f32x4*)(cin + 256 * j);
; #pragma unroll
;                 for (int kp = 0; kp < 3; ++kp) v[j] += *(const f32x4*)(pp + (size_t)kp * NCTX * 1024 + 256 * j);
;                 *(f32x4*)(xo + 256 * j) = v[j];
;             }
;         }
.LBB0_160:
	v_readlane_b32 s24, v253, 15
	s_add_i32 s24, s6, 0xffff8000
	s_cmp_lt_i32 s6, 0x8000
	s_cselect_b64 s[0:1], -1, 0
	s_and_b64 s[12:13], s[0:1], exec
	v_readlane_b32 s16, v251, 0
	s_cselect_b32 s13, s7, 0
	s_cselect_b32 s12, s6, s24
	v_readlane_b32 s22, v251, 6
	v_readlane_b32 s23, v251, 7
	s_cselect_b32 s14, s23, s29
	s_cselect_b32 s15, s22, s28
	s_lshl_b64 s[12:13], s[12:13], 12
	s_add_u32 s12, s15, s12
	s_addc_u32 s13, s14, s13
	v_lshlrev_b32_e32 v192, 2, v16
	s_waitcnt vmcnt(4)
	v_mov_b32_e32 v0, v152
	v_mov_b32_e32 v1, v153
	v_mov_b32_e32 v2, v154
	v_mov_b32_e32 v3, v155
	v_mov_b32_e32 v8, v156
	v_mov_b32_e32 v9, v157
	v_mov_b32_e32 v10, v158
	v_mov_b32_e32 v11, v159
	v_mov_b32_e32 v4, v160
	v_mov_b32_e32 v5, v161
	v_mov_b32_e32 v6, v162
	v_mov_b32_e32 v7, v163
	v_mov_b32_e32 v12, v164
	v_mov_b32_e32 v13, v165
	v_mov_b32_e32 v14, v166
	v_mov_b32_e32 v15, v167
	v_readlane_b32 s12, v254, 31
	v_readlane_b32 s13, v254, 32
	v_readlane_b32 s25, v253, 16
	s_xor_b64 s[12:13], s[12:13], -1
	s_or_b64 s[0:1], s[12:13], s[0:1]
	v_writelane_b32 v253, s24, 15
	s_and_b64 vcc, exec, s[0:1]
	v_readlane_b32 s17, v251, 1
	v_writelane_b32 v253, s25, 16
	v_readlane_b32 s18, v251, 2
	v_readlane_b32 s19, v251, 3
	v_readlane_b32 s20, v251, 4
	v_readlane_b32 s21, v251, 5
	s_cbranch_vccnz .LBB0_162
	s_lshl_b64 s[0:1], s[24:25], 12
	v_lshl_add_u64 v[44:45], v[18:19], 0, s[0:1]
	s_waitcnt vmcnt(0)
	v_lshl_add_u64 v[14:15], v[30:31], 0, s[0:1]
	global_load_dwordx4 v[0:3], v[44:45], off
	global_load_dwordx4 v[4:7], v[14:15], off
	v_add_co_u32_e32 v12, vcc, 0x400000, v14
	v_lshl_add_u64 v[34:35], v[20:21], 0, s[0:1]
	s_nop 0
	v_addc_co_u32_e32 v13, vcc, 0, v15, vcc
	v_add_co_u32_e32 v36, vcc, 0x800000, v14
	s_waitcnt vmcnt(0)
	v_pk_add_f32 v[6:7], v[2:3], v[6:7]
	v_pk_add_f32 v[4:5], v[0:1], v[4:5]
	global_load_dwordx4 v[0:3], v[12:13], off
	v_addc_co_u32_e32 v37, vcc, 0, v15, vcc
	s_waitcnt vmcnt(0)
	v_pk_add_f32 v[6:7], v[6:7], v[2:3]
	v_pk_add_f32 v[4:5], v[4:5], v[0:1]
	global_load_dwordx4 v[0:3], v[36:37], off
	s_waitcnt vmcnt(0)
	v_pk_add_f32 v[2:3], v[6:7], v[2:3]
	v_pk_add_f32 v[0:1], v[4:5], v[0:1]
	global_store_dwordx4 v[34:35], v[0:3], off
	global_load_dwordx4 v[4:7], v[44:45], off offset:1024
	global_load_dwordx4 v[8:11], v[14:15], off offset:1024
	s_waitcnt vmcnt(0)
	v_pk_add_f32 v[10:11], v[6:7], v[10:11]
	v_pk_add_f32 v[8:9], v[4:5], v[8:9]
	global_load_dwordx4 v[4:7], v[12:13], off offset:1024
	s_waitcnt vmcnt(0)
	v_pk_add_f32 v[10:11], v[10:11], v[6:7]
	v_pk_add_f32 v[8:9], v[8:9], v[4:5]
	global_load_dwordx4 v[4:7], v[36:37], off offset:1024
	s_waitcnt vmcnt(0)
	v_pk_add_f32 v[10:11], v[10:11], v[6:7]
	v_pk_add_f32 v[8:9], v[8:9], v[4:5]
	global_store_dwordx4 v[34:35], v[8:11], off offset:1024
	global_load_dwordx4 v[4:7], v[44:45], off offset:2048
	global_load_dwordx4 v[40:43], v[14:15], off offset:2048
	s_waitcnt vmcnt(0)
	v_pk_add_f32 v[42:43], v[6:7], v[42:43]
	v_pk_add_f32 v[40:41], v[4:5], v[40:41]
	global_load_dwordx4 v[4:7], v[12:13], off offset:2048
	s_waitcnt vmcnt(0)
	v_pk_add_f32 v[42:43], v[42:43], v[6:7]
	v_pk_add_f32 v[40:41], v[40:41], v[4:5]
	global_load_dwordx4 v[4:7], v[36:37], off offset:2048
	s_waitcnt vmcnt(0)
	v_pk_add_f32 v[6:7], v[42:43], v[6:7]
	v_pk_add_f32 v[4:5], v[40:41], v[4:5]
	global_store_dwordx4 v[34:35], v[4:7], off offset:2048
	global_load_dwordx4 v[40:43], v[44:45], off offset:3072
	s_nop 0
	global_load_dwordx4 v[44:47], v[14:15], off offset:3072
	s_waitcnt vmcnt(0)
	v_pk_add_f32 v[42:43], v[42:43], v[46:47]
	global_load_dwordx4 v[12:15], v[12:13], off offset:3072
	v_pk_add_f32 v[40:41], v[40:41], v[44:45]
	s_waitcnt vmcnt(0)
	v_pk_add_f32 v[42:43], v[42:43], v[14:15]
	v_pk_add_f32 v[40:41], v[40:41], v[12:13]
	global_load_dwordx4 v[12:15], v[36:37], off offset:3072
	s_waitcnt vmcnt(0)
	v_pk_add_f32 v[14:15], v[42:43], v[14:15]
	v_pk_add_f32 v[12:13], v[40:41], v[12:13]
	global_store_dwordx4 v[34:35], v[12:15], off offset:3072
; __device__ __forceinline__ void phase_norm(const Frame& F, const Params& P, int l, int which, int nrows, bf16_t* HB) {
;     ...
;         const int mb = (row < NLAT) ? (row >> 13) : 4;
;         const float* sh = MOD + mb * 6144 + (which ? 3072 : 0); const float* sc = sh + 1024;
;         f32x4 v[4]; float ss = 0.f;
; #pragma unroll
;         for (int j = 0; j < 4; ++j) v[j] = *(const f32x4*)(xr + 4 * F.lane + 256 * j);
;         if (l == 0 && which == 1 && row >= NLAT) {
;             const float* cin = P.in[2] + (size_t)(row - NLAT) * 1024 + 4 * F.lane;
;             const float* pp = (const float*)(P.ws + WS_AR + AR_PG4) + (size_t)(row - NLAT) * 1024 + 4 * F.lane;
;             float* xo = (float*)(P.ws + WS_XC) + (size_t)(row - NLAT) * 1024 + 4 * F.lane;
; #pragma unroll
;             for (int j = 0; j < 4; ++j) {
;                 v[j] = *(const f32x4*)(cin + 256 * j);
; #pragma unroll
;                 for (int kp = 0; kp < 3; ++kp) v[j] += *(const f32x4*)(pp + (size_t)kp * NCTX * 1024 + 256 * j);
;                 *(f32x4*)(xo + 256 * j) = v[j];
;             }
;         }
;         if (l == 1 && which == 0 && row >= NLAT) {
;             const float* pp = (const float*)(P.ws + WS_AR + AR_PART) + (size_t)(row - NLAT) * 1024 + 4 * F.lane;
; #pragma unroll
;             for (int kp = 0; kp < 4; ++kp)
; #pragma unroll
;                 for (int j = 0; j < 4; ++j) v[j] += *(const f32x4*)(pp + (size_t)kp * NCTX * 1024 + 256 * j);
;         }
; #pragma unroll
;         for (int j = 0; j < 4; ++j) ss += (v[j][0] * v[j][0] + v[j][1] * v[j][1]) + (v[j][2] * v[j][2] + v[j][3] * v[j][3]);
;         ss = wave_sum(ss); const float rinv = rsqrtf(ss * (1.0f / 1024.0f) + EPS);
; #pragma unroll
;         for (int j = 0; j < 4; ++j) {
;             const int col = 4 * F.lane + 256 * j;
;             const f32x4 g = *(const f32x4*)(gn + col), s1 = *(const f32x4*)(sc + col), s0 = *(const f32x4*)(sh + col);
;             const f32x4 y = v[j] * rinv * g * (s1 + 1.0f) + s0;
;             u32x2 w; w.x = cvt_pk_bf16(y[0], y[1]); w.y = cvt_pk_bf16(y[2], y[3]);
;             *(u32x2*)(H + (size_t)row * 1024 + col) = w;
;             if (HB && (((row + 2) & 127) < 4)) *(u32x2*)(HB + (size_t)(4 * ((row + 2) >> 7) + ((row + 2) & 127)) * 1024 + col) = w;
;         }
.LBB0_162:
	s_min_i32 s0, s6, 0x8000
	s_ashr_i32 s0, s0, 13
	s_mulk_i32 s0, 0x1800
	s_ashr_i32 s1, s0, 31
	s_lshl_b64 s[0:1], s[0:1], 2
	v_readlane_b32 s12, v253, 63
	s_add_u32 s0, s12, s0
	v_readlane_b32 s12, v254, 1
	s_addc_u32 s1, s12, s1
	s_add_u32 s12, s0, 0x1000
	s_addc_u32 s13, s1, 0
	global_load_dwordx4 v[40:43], v[22:23], off
	s_nop 0
	global_load_dwordx4 v[44:47], v192, s[12:13]
	global_load_dwordx4 v[48:51], v192, s[0:1]
	global_load_dwordx4 v[100:103], v[24:25], off
	global_load_dwordx4 v[104:107], v17, s[12:13]
	global_load_dwordx4 v[108:111], v192, s[0:1] offset:1024
	global_load_dwordx4 v[112:115], v[26:27], off
	global_load_dwordx4 v[116:119], v38, s[12:13]
	global_load_dwordx4 v[120:123], v192, s[0:1] offset:2048
	global_load_dwordx4 v[124:127], v[28:29], off
	global_load_dwordx4 v[128:131], v39, s[12:13]
	global_load_dwordx4 v[132:135], v192, s[0:1] offset:3072
	s_add_i32 s16, s6, s8
	v_readlane_b32 s17, v253, 35
	s_cmp_lt_i32 s16, s17
	s_cselect_b32 s16, s16, s6
	s_add_i32 s17, s16, 0xffff8000
	s_cmp_lt_i32 s16, 0x8000
	s_cselect_b32 s18, s22, s28
	s_cselect_b32 s19, s23, s29
	s_cselect_b32 s16, s16, s17
	s_lshl_b32 s16, s16, 12
	s_add_u32 s18, s18, s16
	s_addc_u32 s19, s19, 0
	global_load_dwordx4 v[152:155], v192, s[18:19]
	global_load_dwordx4 v[156:159], v192, s[18:19] offset:1024
	global_load_dwordx4 v[160:163], v192, s[18:19] offset:2048
	global_load_dwordx4 v[164:167], v192, s[18:19] offset:3072
	s_waitcnt vmcnt(4)
	v_mul_f32_e32 v34, v1, v1
	v_mul_f32_e32 v35, v3, v3
	v_fmac_f32_e32 v34, v0, v0
	v_fmac_f32_e32 v35, v2, v2
	v_add_f32_e32 v34, v34, v35
	v_mul_f32_e32 v35, v9, v9
	v_mul_f32_e32 v36, v11, v11
	v_fmac_f32_e32 v35, v8, v8
	v_fmac_f32_e32 v36, v10, v10
	v_add_f32_e32 v35, v35, v36
	v_add_f32_e32 v34, v34, v35
	v_mul_f32_e32 v35, v5, v5
	v_mul_f32_e32 v36, v7, v7
	v_fmac_f32_e32 v35, v4, v4
	v_fmac_f32_e32 v36, v6, v6
	v_add_f32_e32 v35, v35, v36
	v_add_f32_e32 v34, v35, v34
	v_mul_f32_e32 v35, v13, v13
	v_mul_f32_e32 v36, v15, v15
	v_fmac_f32_e32 v35, v12, v12
	v_fmac_f32_e32 v36, v14, v14
	v_add_f32_e32 v35, v35, v36
	v_add_f32_e32 v34, v35, v34
	ds_swizzle_b32 v35, v34 offset:swizzle(SWAP,1)
	s_mov_b32 s14, 0x800000
	s_waitcnt lgkmcnt(0)
	v_add_f32_e32 v34, v34, v35
	ds_swizzle_b32 v35, v34 offset:swizzle(SWAP,2)
	s_waitcnt lgkmcnt(0)
	v_add_f32_e32 v34, v34, v35
	ds_swizzle_b32 v35, v34 offset:swizzle(SWAP,4)
	s_waitcnt lgkmcnt(0)
	v_add_f32_e32 v34, v34, v35
	ds_swizzle_b32 v35, v34 offset:swizzle(SWAP,8)
	s_waitcnt lgkmcnt(0)
	v_add_f32_e32 v34, v34, v35
	ds_swizzle_b32 v35, v34 offset:swizzle(SWAP,16)
	s_waitcnt lgkmcnt(0)
	v_add_f32_e32 v34, v34, v35
	v_mov_b32_e32 v35, v34
	s_nop 1
	v_permlane32_swap_b32_e32 v34, v35
	v_add_f32_e32 v34, v34, v35
	v_fmamk_f32 v34, v34, 0x3a800000, v226
	v_cmp_gt_f32_e32 vcc, s14, v34
	v_mul_f32_e32 v35, 0x4b800000, v34
	s_add_i32 s14, s6, 2
	v_cndmask_b32_e32 v34, v34, v35, vcc
	v_rsq_f32_e32 v34, v34
	s_and_b32 s18, s14, 0x7f
	s_cmp_lt_u32 s18, 4
	s_cselect_b64 s[16:17], -1, 0
	s_ashr_i32 s14, s14, 5
	s_and_b32 s14, s14, -4
	v_mul_f32_e32 v35, 0x45800000, v34
	s_or_b32 s14, s14, s18
	v_cndmask_b32_e32 v34, v34, v35, vcc
	s_ashr_i32 s15, s14, 31
	s_lshl_b64 s[14:15], s[14:15], 11
	v_pk_mul_f32 v[2:3], v[2:3], v[34:35] op_sel_hi:[1,0]
	v_pk_mul_f32 v[0:1], v[0:1], v[34:35] op_sel_hi:[1,0]
	s_add_u32 s14, s2, s14
	s_addc_u32 s15, s3, s15
	v_pk_mul_f32 v[0:1], v[40:41], v[0:1]
	v_pk_mul_f32 v[2:3], v[42:43], v[2:3]
	v_pk_add_f32 v[36:37], v[46:47], 1.0 op_sel_hi:[1,0]
	v_pk_add_f32 v[40:41], v[44:45], 1.0 op_sel_hi:[1,0]
	v_pk_fma_f32 v[36:37], v[36:37], v[2:3], v[50:51]
	v_pk_fma_f32 v[0:1], v[40:41], v[0:1], v[48:49]
	s_cmp_gt_u32 s18, 3
	v_cvt_pk_bf16_f32 v2, v0, v1
	v_cvt_pk_bf16_f32 v3, v36, v37
	v_lshlrev_b32_e32 v0, 1, v16
	global_store_dwordx2 v[32:33], v[2:3], off
	s_cbranch_scc1 .LBB0_164
	v_mov_b32_e32 v1, v193
	v_lshl_add_u64 v[36:37], s[14:15], 0, v[0:1]
	global_store_dwordx2 v[36:37], v[2:3], off
.LBB0_164:
	v_lshl_add_u64 v[2:3], s[0:1], 0, v[192:193]
	v_mov_b32_e32 v35, v34
	v_mov_b32_e32 v36, v34
	v_mov_b32_e32 v37, v34
	v_pk_mul_f32 v[10:11], v[10:11], v[36:37]
	v_pk_mul_f32 v[8:9], v[8:9], v[34:35]
	v_cndmask_b32_e64 v1, 0, 1, s[16:17]
	v_cmp_ne_u32_e64 s[0:1], 1, v1
	s_andn2_b64 vcc, exec, s[16:17]
	v_mov_b32_e32 v40, v100
	v_mov_b32_e32 v41, v101
	v_mov_b32_e32 v42, v102
	v_mov_b32_e32 v43, v103
	v_mov_b32_e32 v44, v104
	v_mov_b32_e32 v45, v105
	v_mov_b32_e32 v46, v106
	v_mov_b32_e32 v47, v107
	v_mov_b32_e32 v48, v108
	v_mov_b32_e32 v49, v109
	v_mov_b32_e32 v50, v110
	v_mov_b32_e32 v51, v111
	v_pk_mul_f32 v[10:11], v[10:11], v[42:43]
	v_pk_mul_f32 v[8:9], v[8:9], v[40:41]
	v_pk_add_f32 v[40:41], v[46:47], 1.0 op_sel_hi:[1,0]
	v_pk_add_f32 v[42:43], v[44:45], 1.0 op_sel_hi:[1,0]
	v_pk_fma_f32 v[10:11], v[10:11], v[40:41], v[50:51]
	v_pk_fma_f32 v[8:9], v[8:9], v[42:43], v[48:49]
	s_nop 0
	v_cvt_pk_bf16_f32 v8, v8, v9
	v_cvt_pk_bf16_f32 v9, v10, v11
	global_store_dwordx2 v[32:33], v[8:9], off offset:512
	s_cbranch_vccnz .LBB0_166
	v_mov_b32_e32 v1, v193
	v_lshl_add_u64 v[10:11], s[14:15], 0, v[0:1]
	global_store_dwordx2 v[10:11], v[8:9], off offset:512
.LBB0_166:
	s_nop 0
	v_pk_mul_f32 v[6:7], v[6:7], v[36:37]
	v_pk_mul_f32 v[4:5], v[4:5], v[34:35]
	s_and_b64 vcc, exec, s[0:1]
	v_mov_b32_e32 v8, v112
	v_mov_b32_e32 v9, v113
	v_mov_b32_e32 v10, v114
	v_mov_b32_e32 v11, v115
	v_mov_b32_e32 v40, v116
	v_mov_b32_e32 v41, v117
	v_mov_b32_e32 v42, v118
	v_mov_b32_e32 v43, v119
	v_mov_b32_e32 v44, v120
	v_mov_b32_e32 v45, v121
	v_mov_b32_e32 v46, v122
	v_mov_b32_e32 v47, v123
	v_pk_mul_f32 v[6:7], v[6:7], v[10:11]
	v_pk_mul_f32 v[4:5], v[4:5], v[8:9]
	v_pk_add_f32 v[8:9], v[42:43], 1.0 op_sel_hi:[1,0]
	v_pk_add_f32 v[10:11], v[40:41], 1.0 op_sel_hi:[1,0]
	v_pk_fma_f32 v[6:7], v[6:7], v[8:9], v[46:47]
	v_pk_fma_f32 v[4:5], v[4:5], v[10:11], v[44:45]
	s_nop 0
	v_cvt_pk_bf16_f32 v4, v4, v5
	v_cvt_pk_bf16_f32 v5, v6, v7
	global_store_dwordx2 v[32:33], v[4:5], off offset:1024
	s_cbranch_vccnz .LBB0_168
	v_mov_b32_e32 v1, v193
	v_lshl_add_u64 v[6:7], s[14:15], 0, v[0:1]
	global_store_dwordx2 v[6:7], v[4:5], off offset:1024

; __device__ __forceinline__ void phase_norm(const Frame& F, const Params& P, int l, int which, int nrows, bf16_t* HB) {
;     ...
;     for (int row = gw; row < nrows; row += NGW) {
.LBB0_170:
	s_waitcnt vmcnt(0)
	s_mov_b64 s[0:1], 0

; __device__ __forceinline__ void phase_norm(const Frame& F, const Params& P, int l, int which, int nrows, bf16_t* HB) {
;     const float* xl = (l == 0 && which == 0) ? P.in[0] : P.out; const float* xc = (l == 0 && which == 0) ? P.in[2] : (const float*)(P.ws + WS_XC);
;     const float* gn = P.in[6] + (l * 2 + which) * 1024; const float* MOD = (const float*)(P.ws + WS_MOD) + l * 5 * 6144;
;     bf16_t* H = (bf16_t*)(P.ws + WS_H);
;     const int gw = F.bid * 8 + F.wave, NGW = F.G * 8;
;     for (int row = gw; row < nrows; row += NGW) {
;         const float* xr = (row < NLAT) ? xl + (size_t)row * 1024 : xc + (size_t)(row - NLAT) * 1024;
;         const int mb = (row < NLAT) ? (row >> 13) : 4;
;         const float* sh = MOD + mb * 6144 + (which ? 3072 : 0); const float* sc = sh + 1024;
;         f32x4 v[4]; float ss = 0.f;
; #pragma unroll
;         for (int j = 0; j < 4; ++j) v[j] = *(const f32x4*)(xr + 4 * F.lane + 256 * j);
.LBB0_566:
	s_andn2_b64 vcc, exec, s[0:1]
	s_cbranch_vccnz .LBB0_693
	v_readlane_b32 s0, v254, 34
	v_readlane_b32 s1, v254, 35
	s_lshl_b32 s0, s0, 3
	v_readlane_b32 s1, v254, 37
	s_add_i32 s20, s0, s1
	v_readlane_b32 s0, v254, 36
	s_lshl_b32 s24, s0, 3
	s_cmp_gt_i32 s20, 0x83ff
	s_cbranch_scc1 .LBB0_573
	v_readlane_b32 s0, v253, 56
	v_lshlrev_b32_e32 v192, 4, v194
	v_readlane_b32 s1, v253, 57
	s_ashr_i32 s21, s20, 31
	v_readlane_b32 s2, v253, 11
	v_lshl_add_u64 v[18:19], s[0:1], 0, v[192:193]
	v_readlane_b32 s0, v251, 39
	v_readlane_b32 s1, v251, 40
	v_lshlrev_b32_e32 v16, 2, v194
	v_or_b32_e32 v0, 0x100, v16
	v_lshl_add_u64 v[20:21], s[0:1], 0, v[192:193]
	s_lshl_b64 s[0:1], s[20:21], 11
	s_add_u32 s0, s2, s0
	v_readlane_b32 s2, v253, 12
	v_or_b32_e32 v2, 0x200, v16
	v_or_b32_e32 v4, 0x300, v16
	v_lshlrev_b32_e32 v192, 3, v194
	s_addc_u32 s1, s2, s1
	s_ashr_i32 s25, s24, 31
	v_lshl_add_u64 v[22:23], s[0:1], 0, v[192:193]
	s_lshl_b64 s[0:1], s[24:25], 11
	v_lshlrev_b32_e32 v17, 2, v0
	v_lshlrev_b32_e32 v24, 2, v2
	v_lshlrev_b32_e32 v25, 2, v4
	s_mov_b64 s[6:7], s[20:21]
	v_lshlrev_b32_e32 v26, 2, v16
	s_add_i32 s17, s6, 0xffff8000
	v_readlane_b32 s14, v254, 23
	v_readlane_b32 s15, v254, 22
	v_readlane_b32 s18, v254, 26
	v_readlane_b32 s19, v254, 25
	s_cmp_lt_i32 s6, 0x8000
	s_cselect_b32 s14, s14, s18
	s_cselect_b32 s15, s15, s19
	s_cselect_b32 s16, s6, s17
	s_lshl_b32 s16, s16, 12
	s_add_u32 s14, s14, s16
	s_addc_u32 s15, s15, 0
	global_load_dwordx4 v[152:155], v26, s[14:15]
	global_load_dwordx4 v[156:159], v26, s[14:15] offset:1024
	global_load_dwordx4 v[160:163], v26, s[14:15] offset:2048
	global_load_dwordx4 v[164:167], v26, s[14:15] offset:3072
	s_waitcnt vmcnt(0)
	s_branch .LBB0_571

; __device__ __forceinline__ void phase_norm(const Frame& F, const Params& P, int l, int which, int nrows, bf16_t* HB) {
;     ...
;     for (int row = gw; row < nrows; row += NGW) {
;         const float* xr = (row < NLAT) ? xl + (size_t)row * 1024 : xc + (size_t)(row - NLAT) * 1024;
;         const int mb = (row < NLAT) ? (row >> 13) : 4;
;         const float* sh = MOD + mb * 6144 + (which ? 3072 : 0); const float* sc = sh + 1024;
;         f32x4 v[4]; float ss = 0.f;
; #pragma unroll
;         for (int j = 0; j < 4; ++j) v[j] = *(const f32x4*)(xr + 4 * F.lane + 256 * j);
;         if (l == 0 && which == 1 && row >= NLAT) {
;             const float* cin = P.in[2] + (size_t)(row - NLAT) * 1024 + 4 * F.lane;
;             const float* pp = (const float*)(P.ws + WS_AR + AR_PG4) + (size_t)(row - NLAT) * 1024 + 4 * F.lane;
;             float* xo = (float*)(P.ws + WS_XC) + (size_t)(row - NLAT) * 1024 + 4 * F.lane;
; #pragma unroll
;             for (int j = 0; j < 4; ++j) {
;                 v[j] = *(const f32x4*)(cin + 256 * j);
; #pragma unroll
;                 for (int kp = 0; kp < 3; ++kp) v[j] += *(const f32x4*)(pp + (size_t)kp * NCTX * 1024 + 256 * j);
;                 *(f32x4*)(xo + 256 * j) = v[j];
;             }
;         }
;         if (l == 1 && which == 0 && row >= NLAT) {
;             const float* pp = (const float*)(P.ws + WS_AR + AR_PART) + (size_t)(row - NLAT) * 1024 + 4 * F.lane;
; #pragma unroll
;             for (int kp = 0; kp < 4; ++kp)
; #pragma unroll
;                 for (int j = 0; j < 4; ++j) v[j] += *(const f32x4*)(pp + (size_t)kp * NCTX * 1024 + 256 * j);
;         }
; #pragma unroll
;         for (int j = 0; j < 4; ++j) ss += (v[j][0] * v[j][0] + v[j][1] * v[j][1]) + (v[j][2] * v[j][2] + v[j][3] * v[j][3]);
;         ss = wave_sum(ss); const float rinv = rsqrtf(ss * (1.0f / 1024.0f) + EPS);
; #pragma unroll
;         for (int j = 0; j < 4; ++j) {
;             const int col = 4 * F.lane + 256 * j;
;             const f32x4 g = *(const f32x4*)(gn + col), s1 = *(const f32x4*)(sc + col), s0 = *(const f32x4*)(sh + col);
;             const f32x4 y = v[j] * rinv * g * (s1 + 1.0f) + s0;
;             u32x2 w; w.x = cvt_pk_bf16(y[0], y[1]); w.y = cvt_pk_bf16(y[2], y[3]);
;             *(u32x2*)(H + (size_t)row * 1024 + col) = w;
.LBB0_570:
	s_min_i32 s2, s6, 0x8000
	s_ashr_i32 s2, s2, 13
	s_mulk_i32 s2, 0x1800
	s_ashr_i32 s3, s2, 31
	s_lshl_b64 s[2:3], s[2:3], 2
	v_readlane_b32 s8, v253, 62
	s_add_u32 s8, s8, s2
	v_readlane_b32 s2, v254, 0
	s_addc_u32 s9, s2, s3
	s_add_u32 s10, s8, 0x1000
	global_load_dwordx4 v[28:31], v[18:19], off
	s_addc_u32 s11, s9, 0
	global_load_dwordx4 v[32:35], v26, s[10:11]
	global_load_dwordx4 v[36:39], v26, s[8:9]
	global_load_dwordx4 v[100:103], v[18:19], off offset:1024
	global_load_dwordx4 v[104:107], v17, s[10:11]
	global_load_dwordx4 v[108:111], v26, s[8:9] offset:1024
	global_load_dwordx4 v[112:115], v[18:19], off offset:2048
	global_load_dwordx4 v[116:119], v24, s[10:11]
	global_load_dwordx4 v[120:123], v26, s[8:9] offset:2048
	global_load_dwordx4 v[124:127], v[18:19], off offset:3072
	global_load_dwordx4 v[128:131], v25, s[10:11]
	global_load_dwordx4 v[132:135], v26, s[8:9] offset:3072
	s_add_i32 s16, s6, s24
	s_cmp_lt_i32 s16, 0x8400
	s_cselect_b32 s16, s16, s6
	s_add_i32 s17, s16, 0xffff8000
	v_readlane_b32 s14, v254, 23
	v_readlane_b32 s15, v254, 22
	v_readlane_b32 s18, v254, 26
	v_readlane_b32 s19, v254, 25
	s_cmp_lt_i32 s16, 0x8000
	s_cselect_b32 s14, s14, s18
	s_cselect_b32 s15, s15, s19
	s_cselect_b32 s16, s16, s17
	s_lshl_b32 s16, s16, 12
	s_add_u32 s14, s14, s16
	s_addc_u32 s15, s15, 0
	global_load_dwordx4 v[152:155], v26, s[14:15]
	global_load_dwordx4 v[156:159], v26, s[14:15] offset:1024
	global_load_dwordx4 v[160:163], v26, s[14:15] offset:2048
	global_load_dwordx4 v[164:167], v26, s[14:15] offset:3072
	s_waitcnt vmcnt(4)
	v_mul_f32_e32 v27, v13, v13
	v_mul_f32_e32 v40, v15, v15
	v_mul_f32_e32 v41, v9, v9
	v_mul_f32_e32 v42, v11, v11
	v_mul_f32_e32 v43, v5, v5
	v_mul_f32_e32 v44, v7, v7
	v_fmac_f32_e32 v27, v12, v12
	v_fmac_f32_e32 v40, v14, v14
	v_fmac_f32_e32 v41, v8, v8
	v_fmac_f32_e32 v42, v10, v10
	v_mul_f32_e32 v45, v1, v1
	v_mul_f32_e32 v46, v3, v3
	v_fmac_f32_e32 v43, v4, v4
	v_fmac_f32_e32 v44, v6, v6
	v_add_f32_e32 v27, v27, v40
	v_add_f32_e32 v40, v41, v42
	v_fmac_f32_e32 v45, v0, v0
	v_fmac_f32_e32 v46, v2, v2
	v_add_f32_e32 v41, v43, v44
	v_add_f32_e32 v27, v27, v40
	v_add_f32_e32 v42, v45, v46
	v_add_f32_e32 v27, v41, v27
	v_add_f32_e32 v27, v42, v27
	ds_swizzle_b32 v40, v27 offset:swizzle(SWAP,1)
	s_add_u32 s6, s6, s24
	s_addc_u32 s7, s7, s25
	s_cmp_lt_i32 s6, 0x8400
	s_waitcnt lgkmcnt(0)
	v_add_f32_e32 v27, v27, v40
	ds_swizzle_b32 v40, v27 offset:swizzle(SWAP,2)
	s_waitcnt lgkmcnt(0)
	v_add_f32_e32 v27, v27, v40
	ds_swizzle_b32 v40, v27 offset:swizzle(SWAP,4)
	s_waitcnt lgkmcnt(0)
	v_add_f32_e32 v27, v27, v40
	ds_swizzle_b32 v40, v27 offset:swizzle(SWAP,8)
	s_waitcnt lgkmcnt(0)
	v_add_f32_e32 v27, v27, v40
	ds_swizzle_b32 v40, v27 offset:swizzle(SWAP,16)
	s_waitcnt lgkmcnt(0)
	v_add_f32_e32 v27, v27, v40
	v_mov_b32_e32 v40, v27
	s_nop 1
	v_permlane32_swap_b32_e32 v27, v40
	v_add_f32_e32 v27, v27, v40
	v_fmamk_f32 v27, v27, 0x3a800000, v226
	v_mul_f32_e32 v40, 0x4b800000, v27
	v_cmp_gt_f32_e32 vcc, s12, v27
	s_nop 1
	v_cndmask_b32_e32 v27, v27, v40, vcc
	v_rsq_f32_e32 v27, v27
	s_nop 0
	v_mul_f32_e32 v40, 0x45800000, v27
	v_cndmask_b32_e32 v40, v27, v40, vcc
	v_pk_mul_f32 v[14:15], v[14:15], v[40:41] op_sel_hi:[1,0]
	v_pk_mul_f32 v[12:13], v[12:13], v[40:41] op_sel_hi:[1,0]
	v_pk_mul_f32 v[10:11], v[10:11], v[40:41] op_sel_hi:[1,0]
	v_pk_mul_f32 v[8:9], v[8:9], v[40:41] op_sel_hi:[1,0]
	v_pk_mul_f32 v[6:7], v[6:7], v[40:41] op_sel_hi:[1,0]
	v_pk_mul_f32 v[4:5], v[4:5], v[40:41] op_sel_hi:[1,0]
	v_pk_mul_f32 v[2:3], v[2:3], v[40:41] op_sel_hi:[1,0]
	v_pk_mul_f32 v[0:1], v[0:1], v[40:41] op_sel_hi:[1,0]
	v_pk_mul_f32 v[12:13], v[28:29], v[12:13]
	v_pk_mul_f32 v[14:15], v[30:31], v[14:15]
	v_pk_add_f32 v[28:29], v[34:35], 1.0 op_sel_hi:[1,0]
	v_pk_add_f32 v[30:31], v[32:33], 1.0 op_sel_hi:[1,0]
	v_pk_fma_f32 v[14:15], v[28:29], v[14:15], v[38:39]
	v_pk_fma_f32 v[12:13], v[30:31], v[12:13], v[36:37]
	s_nop 0
	v_cvt_pk_bf16_f32 v12, v12, v13
	v_cvt_pk_bf16_f32 v13, v14, v15
	global_store_dwordx2 v[22:23], v[12:13], off
	s_nop 0
	v_mov_b32_e32 v12, v100
	v_mov_b32_e32 v13, v101
	v_mov_b32_e32 v14, v102
	v_mov_b32_e32 v15, v103
	v_pk_mul_f32 v[8:9], v[12:13], v[8:9]
	v_pk_mul_f32 v[10:11], v[14:15], v[10:11]
	v_mov_b32_e32 v28, v104
	v_mov_b32_e32 v29, v105
	v_mov_b32_e32 v30, v106
	v_mov_b32_e32 v31, v107
	v_pk_add_f32 v[12:13], v[30:31], 1.0 op_sel_hi:[1,0]
	v_pk_add_f32 v[14:15], v[28:29], 1.0 op_sel_hi:[1,0]
	v_mov_b32_e32 v32, v108
	v_mov_b32_e32 v33, v109
	v_mov_b32_e32 v34, v110
	v_mov_b32_e32 v35, v111
	v_pk_fma_f32 v[10:11], v[12:13], v[10:11], v[34:35]
	v_pk_fma_f32 v[8:9], v[14:15], v[8:9], v[32:33]
	s_nop 0
	v_cvt_pk_bf16_f32 v8, v8, v9
	v_cvt_pk_bf16_f32 v9, v10, v11
	global_store_dwordx2 v[22:23], v[8:9], off offset:512
	s_nop 0
	v_mov_b32_e32 v8, v112
	v_mov_b32_e32 v9, v113
	v_mov_b32_e32 v10, v114
	v_mov_b32_e32 v11, v115
	v_pk_mul_f32 v[4:5], v[8:9], v[4:5]
	v_pk_mul_f32 v[6:7], v[10:11], v[6:7]
	v_mov_b32_e32 v12, v116
	v_mov_b32_e32 v13, v117
	v_mov_b32_e32 v14, v118
	v_mov_b32_e32 v15, v119
	v_pk_add_f32 v[8:9], v[14:15], 1.0 op_sel_hi:[1,0]
	v_pk_add_f32 v[10:11], v[12:13], 1.0 op_sel_hi:[1,0]
	v_mov_b32_e32 v28, v120
	v_mov_b32_e32 v29, v121
	v_mov_b32_e32 v30, v122
	v_mov_b32_e32 v31, v123
	v_pk_fma_f32 v[6:7], v[8:9], v[6:7], v[30:31]
	v_pk_fma_f32 v[4:5], v[10:11], v[4:5], v[28:29]
	s_nop 0
	v_cvt_pk_bf16_f32 v4, v4, v5
	v_cvt_pk_bf16_f32 v5, v6, v7
	global_store_dwordx2 v[22:23], v[4:5], off offset:1024
	s_nop 0
	v_mov_b32_e32 v4, v124
	v_mov_b32_e32 v5, v125
	v_mov_b32_e32 v6, v126
	v_mov_b32_e32 v7, v127
	v_pk_mul_f32 v[0:1], v[0:1], v[4:5]
	v_pk_mul_f32 v[2:3], v[2:3], v[6:7]
	v_mov_b32_e32 v8, v128
	v_mov_b32_e32 v9, v129
	v_mov_b32_e32 v10, v130
	v_mov_b32_e32 v11, v131
	v_pk_add_f32 v[4:5], v[10:11], 1.0 op_sel_hi:[1,0]
	v_pk_add_f32 v[6:7], v[8:9], 1.0 op_sel_hi:[1,0]
	v_mov_b32_e32 v12, v132
	v_mov_b32_e32 v13, v133
	v_mov_b32_e32 v14, v134
	v_mov_b32_e32 v15, v135
	v_pk_fma_f32 v[2:3], v[2:3], v[4:5], v[14:15]
	v_pk_fma_f32 v[0:1], v[0:1], v[6:7], v[12:13]
	s_nop 0
	v_cvt_pk_bf16_f32 v0, v0, v1
	v_cvt_pk_bf16_f32 v1, v2, v3
	global_store_dwordx2 v[22:23], v[0:1], off offset:1536
	v_lshl_add_u64 v[22:23], v[22:23], 0, s[0:1]
	s_cbranch_scc0 .LBB0_573
; __device__ __forceinline__ void prep_s5_part(const Frame& F, const Params& P, int l, int g, int c) {
;     ...
;     for (int idx = F.tid; idx < 2 * 33 * 64; idx += 512) {
;         const int d = idx / (33 * 64), e = (idx / 64) % 33, p = idx % 64; const int gi = (l * 2 + d) * 32 + g;
;         const float lr = lam_re[gi * 64 + p], li = lam_im[gi * 64 + p], dt = expf(log_dt[gi]);
;         const float mag = expf((float)e * lr * dt), ang = (float)e * li * dt; float sn, cs; sincosf(ang, &sn, &cs);
;         apr[idx] = mag * cs; api[idx] = mag * sn;
;     }
;     if (F.tid < 128) { const int d = F.tid >> 6, p = F.tid & 63; const size_t gi = (size_t)((l * 2 + d) * 32 + g);
;         ccr[F.tid] = c_re[(gi * 16 + c) * 64 + p]; cci[F.tid] = c_im[(gi * 16 + c) * 64 + p]; }
; __device__ __forceinline__ void phase_norm(const Frame& F, const Params& P, int l, int which, int nrows, bf16_t* HB) {
;     ...
;     for (int row = gw; row < nrows; row += NGW) {
;         const float* xr = (row < NLAT) ? xl + (size_t)row * 1024 : xc + (size_t)(row - NLAT) * 1024;
;         const int mb = (row < NLAT) ? (row >> 13) : 4;
;         const float* sh = MOD + mb * 6144 + (which ? 3072 : 0); const float* sc = sh + 1024;
;         f32x4 v[4]; float ss = 0.f;
; #pragma unroll
;         for (int j = 0; j < 4; ++j) v[j] = *(const f32x4*)(xr + 4 * F.lane + 256 * j);
.LBB0_571:
	v_readlane_b32 s12, v253, 15
	s_add_i32 s12, s6, 0xffff8000
	s_cmp_lt_i32 s6, 0x8000
	s_cselect_b64 s[2:3], -1, 0
	s_and_b64 s[8:9], s[2:3], exec
	v_readlane_b32 s10, v254, 22
	v_readlane_b32 s11, v254, 25
	s_cselect_b32 s9, s7, 0
	s_cselect_b32 s8, s6, s12
	s_cselect_b32 s10, s10, s11
	v_readlane_b32 s11, v254, 23
	v_readlane_b32 s14, v254, 26
	s_cselect_b32 s11, s11, s14
	s_lshl_b64 s[8:9], s[8:9], 12
	s_add_u32 s8, s11, s8
	s_addc_u32 s9, s10, s9
	v_lshlrev_b32_e32 v26, 2, v16
	s_waitcnt vmcnt(4)
	v_mov_b32_e32 v12, v152
	v_mov_b32_e32 v13, v153
	v_mov_b32_e32 v14, v154
	v_mov_b32_e32 v15, v155
	v_mov_b32_e32 v8, v156
	v_mov_b32_e32 v9, v157
	v_mov_b32_e32 v10, v158
	v_mov_b32_e32 v11, v159
	v_mov_b32_e32 v4, v160
	v_mov_b32_e32 v5, v161
	v_mov_b32_e32 v6, v162
	v_mov_b32_e32 v7, v163
	v_mov_b32_e32 v0, v164
	v_mov_b32_e32 v1, v165
	v_mov_b32_e32 v2, v166
	v_mov_b32_e32 v3, v167
	v_readlane_b32 s8, v253, 32
	v_readlane_b32 s9, v253, 33
	v_readlane_b32 s13, v253, 16
	s_xor_b64 s[8:9], s[8:9], -1
	s_or_b64 s[2:3], s[8:9], s[2:3]
	v_writelane_b32 v253, s12, 15
	s_and_b64 vcc, exec, s[2:3]
	s_nop 0
	v_writelane_b32 v253, s13, 16
	s_cbranch_vccz .LBB0_569
	s_mov_b32 s12, 0x800000
	s_branch .LBB0_570
.LBB0_573:
	s_waitcnt vmcnt(0)
	v_readlane_b32 s0, v253, 32
	v_readlane_b32 s1, v253, 33
	s_andn2_b64 vcc, exec, s[0:1]
	s_cbranch_vccnz .LBB0_693
	v_readlane_b32 s0, v254, 34
	s_cmpk_gt_i32 s0, 0x1ff
	v_readlane_b32 s1, v254, 35
	s_cbranch_scc1 .LBB0_652
	s_movk_i32 s0, 0x1080
	v_cmp_gt_i32_e64 s[6:7], s0, v196
	s_movk_i32 s0, 0x800
	v_cmp_gt_i32_e64 s[10:11], s0, v196
	s_movk_i32 s0, 0x400
	v_cmp_gt_i32_e64 s[12:13], s0, v196
	s_movk_i32 s0, 0xc00
	v_cmp_gt_i32_e64 s[14:15], s0, v196
	v_ashrrev_i32_e32 v0, 1, v196
	v_readlane_b32 s0, v251, 42
	v_and_b32_e32 v0, 0xffffffe0, v0
	v_lshlrev_b32_e32 v192, 4, v194
	v_readlane_b32 s1, v251, 43
	v_add_u32_e32 v9, 64, v0
	v_lshlrev_b32_e32 v0, 2, v196
	v_and_b32_e32 v8, 15, v196
	v_lshl_add_u64 v[10:11], s[0:1], 0, v[192:193]
	s_add_i32 s0, 0, 0x8400
	v_lshrrev_b32_e32 v15, 1, v194
	v_add_u32_e32 v21, s0, v0
	v_lshl_add_u32 v22, v8, 2, s0
	v_readlane_b32 s0, v254, 34
	v_cmp_gt_i32_e64 s[8:9], s53, v196
	v_add_u32_e32 v13, 0, v0
	v_xor_b32_e32 v20, 31, v15
	v_lshlrev_b32_e32 v23, 3, v196
	s_mov_b32 s2, s0
	v_readlane_b32 s1, v254, 35
	s_branch .LBB0_577
